# cvt_pk_bf16 for the P pack in the sample-attention loop
# speedup vs baseline: 1.0010x; 1.0010x over previous
; template <bool SAMPLE>
; DEVI void attn_item(const Params& p, int l, int bq, int h, int qc, char* smem) {
;     ...
;       for (int m = 0; m < 2; ++m) {
;         float mx = s[m][0][0];
; #pragma unroll
;         for (int sub = 0; sub < 4; ++sub)
; #pragma unroll
;           for (int r = 0; r < 4; ++r) mx = fmaxf(mx, s[m][sub][r]);
;         mx = fmaxf(mx, __shfl_xor(mx, 16));
;         mx = fmaxf(mx, __shfl_xor(mx, 32));
;         float mnew = fmaxf(mrun[m], mx);
;         float alpha = exp2f(mrun[m] - mnew);
;         mrun[m] = mnew;
;         float rs = 0.f;
; #pragma unroll
;         for (int sub = 0; sub < 4; ++sub)
; #pragma unroll
;           for (int r = 0; r < 4; ++r) {
;             float pv = exp2f(s[m][sub][r] - mnew);
;             s[m][sub][r] = pv;
;             rs += pv;
;           }
;         lrun[m] = lrun[m] * alpha + rs;
; #pragma unroll
;         for (int vt = 0; vt < 8; ++vt) { o[m][vt][0] *= alpha; o[m][vt][1] *= alpha; o[m][vt][2] *= alpha; o[m][vt][3] *= alpha; }
;         pb[m][0] = pk8(s[m][0], s[m][1]);
;         pb[m][1] = pk8(s[m][2], s[m][3]);
;       }
.LBB0_1071:
	v_and_b32_e32 v152, 64, v208
	v_xor_b32_e32 v3, 16, v208
	v_add_u32_e32 v152, 64, v152
	v_cmp_lt_i32_e32 vcc, v3, v152
	v_max_f32_e32 v153, v112, v112
	s_mov_b32 s20, 0xc2fc0000
	v_cndmask_b32_e32 v3, v208, v3, vcc
	v_lshlrev_b32_e32 v154, 2, v3
	v_xor_b32_e32 v3, 32, v208
	v_cmp_lt_i32_e32 vcc, v3, v152
	s_mov_b32 s19, 0xffff0000
	s_nop 0
	v_cndmask_b32_e32 v3, v208, v3, vcc
	v_lshlrev_b32_e32 v152, 2, v3
	v_max_f32_e32 v3, v113, v113
	v_max_f32_e32 v3, v153, v3
	v_max3_f32 v3, v3, v114, v115
	v_max3_f32 v3, v3, v108, v109
	v_max3_f32 v3, v3, v110, v111
	v_max3_f32 v3, v3, v88, v89
	v_max3_f32 v3, v3, v90, v91
	v_max3_f32 v3, v3, v84, v85
	v_max3_f32 v3, v3, v86, v87
	ds_bpermute_b32 v153, v154, v3
	s_waitcnt lgkmcnt(0)
	v_max_f32_e32 v153, v153, v153
	v_max_f32_e32 v3, v3, v153
	ds_bpermute_b32 v153, v152, v3
	s_waitcnt lgkmcnt(0)
	v_max3_f32 v3, v151, v3, v153
	v_sub_f32_e32 v112, v112, v3
	v_cmp_gt_f32_e32 vcc, s20, v112
	v_sub_f32_e32 v156, v151, v3
	v_sub_f32_e32 v108, v108, v3
	v_cndmask_b32_e32 v151, 0, v228, vcc
	v_add_f32_e32 v112, v112, v151
	v_exp_f32_e32 v112, v112
	v_cndmask_b32_e32 v151, 0, v205, vcc
	v_sub_f32_e32 v88, v88, v3
	v_sub_f32_e32 v84, v84, v3
	v_ldexp_f32 v151, v112, v151
	v_sub_f32_e32 v112, v113, v3
	v_cmp_gt_f32_e32 vcc, s20, v112
	s_nop 1
	v_cndmask_b32_e32 v113, 0, v228, vcc
	v_add_f32_e32 v112, v112, v113
	v_exp_f32_e32 v112, v112
	v_cndmask_b32_e32 v113, 0, v205, vcc
	v_ldexp_f32 v113, v112, v113
	v_sub_f32_e32 v112, v114, v3
	v_cmp_gt_f32_e32 vcc, s20, v112
	s_nop 1
	v_cndmask_b32_e32 v114, 0, v228, vcc
	v_add_f32_e32 v112, v112, v114
	v_exp_f32_e32 v112, v112
	v_cndmask_b32_e32 v114, 0, v205, vcc
	v_ldexp_f32 v153, v112, v114
	v_sub_f32_e32 v112, v115, v3
	v_cmp_gt_f32_e32 vcc, s20, v112
	s_nop 1
	v_cndmask_b32_e32 v114, 0, v228, vcc
	v_add_f32_e32 v112, v112, v114
	v_exp_f32_e32 v112, v112
	v_cndmask_b32_e32 v114, 0, v205, vcc
	v_cmp_gt_f32_e32 vcc, s20, v108
	v_ldexp_f32 v115, v112, v114
	s_nop 0
	v_cndmask_b32_e32 v112, 0, v228, vcc
	v_add_f32_e32 v108, v108, v112
	v_exp_f32_e32 v108, v108
	v_cndmask_b32_e32 v112, 0, v205, vcc
	v_ldexp_f32 v155, v108, v112
	v_sub_f32_e32 v108, v109, v3
	v_cmp_gt_f32_e32 vcc, s20, v108
	s_nop 1
	v_cndmask_b32_e32 v109, 0, v228, vcc
	v_add_f32_e32 v108, v108, v109
	v_exp_f32_e32 v108, v108
	v_cndmask_b32_e32 v109, 0, v205, vcc
	v_ldexp_f32 v109, v108, v109
	v_sub_f32_e32 v108, v110, v3
	v_cmp_gt_f32_e32 vcc, s20, v108
	s_nop 1
	v_cndmask_b32_e32 v110, 0, v228, vcc
	v_add_f32_e32 v108, v108, v110
	v_exp_f32_e32 v108, v108
	v_cndmask_b32_e32 v110, 0, v205, vcc
	v_ldexp_f32 v157, v108, v110
	v_sub_f32_e32 v108, v111, v3
	v_cmp_gt_f32_e32 vcc, s20, v108
	s_nop 1
	v_cndmask_b32_e32 v110, 0, v228, vcc
	v_add_f32_e32 v108, v108, v110
	v_exp_f32_e32 v108, v108
	v_cndmask_b32_e32 v110, 0, v205, vcc
	v_cmp_gt_f32_e32 vcc, s20, v88
	v_ldexp_f32 v159, v108, v110
	s_nop 0
	v_cndmask_b32_e32 v108, 0, v228, vcc
	v_add_f32_e32 v88, v88, v108
	v_exp_f32_e32 v88, v88
	v_cndmask_b32_e32 v108, 0, v205, vcc
	v_ldexp_f32 v111, v88, v108
	v_sub_f32_e32 v88, v89, v3
	v_cmp_gt_f32_e32 vcc, s20, v88
	s_nop 1
	v_cndmask_b32_e32 v89, 0, v228, vcc
	v_add_f32_e32 v88, v88, v89
	v_exp_f32_e32 v88, v88
	v_cndmask_b32_e32 v89, 0, v205, vcc
	v_ldexp_f32 v161, v88, v89
	v_sub_f32_e32 v88, v90, v3
	v_cmp_gt_f32_e32 vcc, s20, v88
	s_nop 1
	v_cndmask_b32_e32 v89, 0, v228, vcc
	v_add_f32_e32 v88, v88, v89
	v_exp_f32_e32 v88, v88
	v_cndmask_b32_e32 v89, 0, v205, vcc
	v_ldexp_f32 v163, v88, v89
	v_sub_f32_e32 v88, v91, v3
	v_cmp_gt_f32_e32 vcc, s20, v88
	s_nop 1
	v_cndmask_b32_e32 v89, 0, v228, vcc
	v_add_f32_e32 v88, v88, v89
	v_exp_f32_e32 v88, v88
	v_cndmask_b32_e32 v89, 0, v205, vcc
	v_cmp_gt_f32_e32 vcc, s20, v84
	v_ldexp_f32 v165, v88, v89
	s_nop 0
	v_cndmask_b32_e32 v88, 0, v228, vcc
	v_add_f32_e32 v84, v84, v88
	v_exp_f32_e32 v84, v84
	v_cndmask_b32_e32 v88, 0, v205, vcc
	v_ldexp_f32 v167, v84, v88
	v_sub_f32_e32 v84, v85, v3
	v_cmp_gt_f32_e32 vcc, s20, v84
	s_nop 1
	v_cndmask_b32_e32 v85, 0, v228, vcc
	v_add_f32_e32 v84, v84, v85
	v_exp_f32_e32 v84, v84
	v_cndmask_b32_e32 v85, 0, v205, vcc
	v_ldexp_f32 v171, v84, v85
	v_sub_f32_e32 v84, v86, v3
	v_cmp_gt_f32_e32 vcc, s20, v84
	s_nop 1
	v_cndmask_b32_e32 v85, 0, v228, vcc
	v_add_f32_e32 v84, v84, v85
	v_exp_f32_e32 v84, v84
	v_cndmask_b32_e32 v85, 0, v205, vcc
	v_cvt_pk_bf16_f32 v89, v153, v115
	v_ldexp_f32 v173, v84, v85
	v_sub_f32_e32 v84, v87, v3
	v_cmp_gt_f32_e32 vcc, s20, v84
	s_nop 1
	v_cndmask_b32_e32 v85, 0, v228, vcc
	v_add_f32_e32 v84, v84, v85
	v_exp_f32_e32 v84, v84
	v_cndmask_b32_e32 v85, 0, v205, vcc
	v_cmp_gt_f32_e32 vcc, s20, v156
	v_cvt_pk_bf16_f32 v88, v151, v113
	v_ldexp_f32 v175, v84, v85
	v_cndmask_b32_e32 v84, 0, v228, vcc
	v_add_f32_e32 v84, v156, v84
	v_exp_f32_e32 v84, v84
	v_cndmask_b32_e32 v85, 0, v205, vcc
	v_ldexp_f32 v176, v84, v85
	v_cvt_pk_bf16_f32 v91, v157, v159
	v_cvt_pk_bf16_f32 v90, v155, v109
	v_cvt_pk_bf16_f32 v87, v173, v175
	v_cvt_pk_bf16_f32 v86, v167, v171
	v_cvt_pk_bf16_f32 v85, v163, v165
	v_cvt_pk_bf16_f32 v84, v111, v161
	v_max_f32_e32 v108, v105, v105
	v_max_f32_e32 v110, v104, v104
	v_max_f32_e32 v108, v110, v108
	v_max3_f32 v108, v108, v106, v107
	v_max3_f32 v108, v108, v100, v101
	v_max3_f32 v108, v108, v102, v103
	v_max3_f32 v108, v108, v96, v97
	v_max3_f32 v108, v108, v98, v99
	v_max3_f32 v108, v108, v92, v93
	v_max3_f32 v108, v108, v94, v95
	ds_bpermute_b32 v110, v154, v108
	v_pk_mul_f32 v[54:55], v[54:55], v[176:177] op_sel_hi:[1,0]
	v_pk_mul_f32 v[52:53], v[52:53], v[176:177] op_sel_hi:[1,0]
	v_pk_mul_f32 v[58:59], v[58:59], v[176:177] op_sel_hi:[1,0]
	v_pk_mul_f32 v[56:57], v[56:57], v[176:177] op_sel_hi:[1,0]
	s_waitcnt lgkmcnt(0)
; template <bool SAMPLE>
; DEVI void attn_item(const Params& p, int l, int bq, int h, int qc, char* smem) {
;     ...
;       for (int m = 0; m < 2; ++m) {
;         float mx = s[m][0][0];
; #pragma unroll
;         for (int sub = 0; sub < 4; ++sub)
; #pragma unroll
;           for (int r = 0; r < 4; ++r) mx = fmaxf(mx, s[m][sub][r]);
;         mx = fmaxf(mx, __shfl_xor(mx, 16));
;         mx = fmaxf(mx, __shfl_xor(mx, 32));
;         float mnew = fmaxf(mrun[m], mx);
;         float alpha = exp2f(mrun[m] - mnew);
;         mrun[m] = mnew;
;         float rs = 0.f;
; #pragma unroll
;         for (int sub = 0; sub < 4; ++sub)
; #pragma unroll
;           for (int r = 0; r < 4; ++r) {
;             float pv = exp2f(s[m][sub][r] - mnew);
;             s[m][sub][r] = pv;
;             rs += pv;
;           }
;         lrun[m] = lrun[m] * alpha + rs;
; #pragma unroll
;         for (int vt = 0; vt < 8; ++vt) { o[m][vt][0] *= alpha; o[m][vt][1] *= alpha; o[m][vt][2] *= alpha; o[m][vt][3] *= alpha; }
;         pb[m][0] = pk8(s[m][0], s[m][1]);
;         pb[m][1] = pk8(s[m][2], s[m][3]);
;       }
	v_max_f32_e32 v110, v110, v110
	v_max_f32_e32 v108, v108, v110
	ds_bpermute_b32 v110, v152, v108
	v_pk_mul_f32 v[62:63], v[62:63], v[176:177] op_sel_hi:[1,0]
	v_pk_mul_f32 v[60:61], v[60:61], v[176:177] op_sel_hi:[1,0]
	v_pk_mul_f32 v[66:67], v[66:67], v[176:177] op_sel_hi:[1,0]
	v_pk_mul_f32 v[64:65], v[64:65], v[176:177] op_sel_hi:[1,0]
	s_waitcnt lgkmcnt(0)
	v_max3_f32 v188, v150, v108, v110
	v_sub_f32_e32 v104, v104, v188
	v_cmp_gt_f32_e32 vcc, s20, v104
	v_sub_f32_e32 v189, v150, v188
	v_sub_f32_e32 v100, v100, v188
	v_cndmask_b32_e32 v108, 0, v228, vcc
	v_add_f32_e32 v104, v104, v108
	v_exp_f32_e32 v104, v104
	v_cndmask_b32_e32 v108, 0, v205, vcc
	v_sub_f32_e32 v102, v102, v188
	v_sub_f32_e32 v96, v96, v188
	v_ldexp_f32 v150, v104, v108
	v_sub_f32_e32 v104, v105, v188
	v_cmp_gt_f32_e32 vcc, s20, v104
	v_sub_f32_e32 v92, v92, v188
	v_pk_mul_f32 v[70:71], v[70:71], v[176:177] op_sel_hi:[1,0]
	v_cndmask_b32_e32 v105, 0, v228, vcc
	v_add_f32_e32 v104, v104, v105
	v_exp_f32_e32 v104, v104
	v_cndmask_b32_e32 v105, 0, v205, vcc
	v_pk_mul_f32 v[68:69], v[68:69], v[176:177] op_sel_hi:[1,0]
	v_pk_mul_f32 v[74:75], v[74:75], v[176:177] op_sel_hi:[1,0]
	v_ldexp_f32 v112, v104, v105
	v_sub_f32_e32 v104, v106, v188
	v_cmp_gt_f32_e32 vcc, s20, v104
	v_pk_mul_f32 v[72:73], v[72:73], v[176:177] op_sel_hi:[1,0]
	v_pk_mul_f32 v[78:79], v[78:79], v[176:177] op_sel_hi:[1,0]
	v_cndmask_b32_e32 v105, 0, v228, vcc
	v_add_f32_e32 v104, v104, v105
	v_exp_f32_e32 v104, v104
	v_cndmask_b32_e32 v105, 0, v205, vcc
	v_pk_mul_f32 v[76:77], v[76:77], v[176:177] op_sel_hi:[1,0]
	v_pk_mul_f32 v[82:83], v[82:83], v[176:177] op_sel_hi:[1,0]
	v_ldexp_f32 v152, v104, v105
	v_sub_f32_e32 v104, v107, v188
	v_cmp_gt_f32_e32 vcc, s20, v104
	v_pk_mul_f32 v[80:81], v[80:81], v[176:177] op_sel_hi:[1,0]
	s_nop 0
	v_cndmask_b32_e32 v105, 0, v228, vcc
	v_add_f32_e32 v104, v104, v105
	v_exp_f32_e32 v104, v104
	v_cndmask_b32_e32 v105, 0, v205, vcc
	v_cmp_gt_f32_e32 vcc, s20, v100
	v_ldexp_f32 v114, v104, v105
	s_nop 0
	v_cndmask_b32_e32 v104, 0, v228, vcc
	v_add_f32_e32 v100, v100, v104
	v_exp_f32_e32 v100, v100
	v_cndmask_b32_e32 v104, 0, v205, vcc
	v_ldexp_f32 v154, v100, v104
	v_sub_f32_e32 v100, v101, v188
	v_cmp_gt_f32_e32 vcc, s20, v100
	s_nop 1
	v_cndmask_b32_e32 v101, 0, v228, vcc
	v_add_f32_e32 v100, v100, v101
	v_cndmask_b32_e32 v101, 0, v205, vcc
	v_cmp_gt_f32_e32 vcc, s20, v102
	v_exp_f32_e32 v100, v100
	s_nop 0
	v_cndmask_b32_e32 v104, 0, v228, vcc
	v_add_f32_e32 v102, v102, v104
	v_exp_f32_e32 v102, v102
	v_cndmask_b32_e32 v104, 0, v205, vcc
	v_ldexp_f32 v108, v100, v101
	v_pk_add_f32 v[100:101], v[150:151], v[112:113]
	v_ldexp_f32 v156, v102, v104
	v_sub_f32_e32 v102, v103, v188
	v_cmp_gt_f32_e32 vcc, s20, v102
	v_pk_add_f32 v[100:101], v[152:153], v[100:101]
	v_mov_b32_e32 v151, v3
	v_cndmask_b32_e32 v103, 0, v228, vcc
	v_add_f32_e32 v102, v102, v103
	v_exp_f32_e32 v102, v102
	v_cndmask_b32_e32 v103, 0, v205, vcc
	v_cmp_gt_f32_e32 vcc, s20, v96
	v_pk_add_f32 v[100:101], v[114:115], v[100:101]
	v_ldexp_f32 v158, v102, v103
	v_cndmask_b32_e32 v102, 0, v228, vcc
	v_add_f32_e32 v96, v96, v102
	v_exp_f32_e32 v96, v96
	v_cndmask_b32_e32 v102, 0, v205, vcc
	v_pk_add_f32 v[100:101], v[154:155], v[100:101]
	v_ldexp_f32 v110, v96, v102
	v_sub_f32_e32 v96, v97, v188
	v_cmp_gt_f32_e32 vcc, s20, v96
	v_pk_add_f32 v[100:101], v[108:109], v[100:101]
	s_nop 0
	v_cndmask_b32_e32 v97, 0, v228, vcc
	v_add_f32_e32 v96, v96, v97
	v_exp_f32_e32 v96, v96
	v_cndmask_b32_e32 v97, 0, v205, vcc
	v_ldexp_f32 v160, v96, v97
	v_sub_f32_e32 v96, v98, v188
	v_cmp_gt_f32_e32 vcc, s20, v96
	v_bfe_u32 v98, v150, 16, 1
	v_add3_u32 v98, v150, v98, s33
	v_cndmask_b32_e32 v97, 0, v228, vcc
	v_add_f32_e32 v96, v96, v97
	v_exp_f32_e32 v96, v96
	v_cndmask_b32_e32 v97, 0, v205, vcc
	v_mov_b32_e32 v150, v188
	v_ldexp_f32 v162, v96, v97
	v_sub_f32_e32 v96, v99, v188
	v_cmp_gt_f32_e32 vcc, s20, v96
	s_nop 1
	v_cndmask_b32_e32 v97, 0, v228, vcc
	v_add_f32_e32 v96, v96, v97
	v_exp_f32_e32 v96, v96
	v_cndmask_b32_e32 v97, 0, v205, vcc
	v_cmp_gt_f32_e32 vcc, s20, v92
	v_ldexp_f32 v164, v96, v97
	s_nop 0
	v_cndmask_b32_e32 v96, 0, v228, vcc
	v_add_f32_e32 v92, v92, v96
	v_exp_f32_e32 v92, v92
	v_cndmask_b32_e32 v96, 0, v205, vcc
	v_ldexp_f32 v166, v92, v96
	v_sub_f32_e32 v92, v93, v188
	v_cmp_gt_f32_e32 vcc, s20, v92
	s_nop 1
	v_cndmask_b32_e32 v93, 0, v228, vcc
	v_add_f32_e32 v92, v92, v93
	v_exp_f32_e32 v92, v92
	v_cndmask_b32_e32 v93, 0, v205, vcc
	v_ldexp_f32 v170, v92, v93
	v_sub_f32_e32 v92, v94, v188
	v_cmp_gt_f32_e32 vcc, s20, v92
	s_nop 1
	v_cndmask_b32_e32 v93, 0, v228, vcc
	v_add_f32_e32 v92, v92, v93
	v_exp_f32_e32 v92, v92
	v_cndmask_b32_e32 v93, 0, v205, vcc
	v_ldexp_f32 v172, v92, v93
	v_sub_f32_e32 v92, v95, v188
	v_cmp_gt_f32_e32 vcc, s20, v92
	v_pk_add_f32 v[94:95], v[156:157], v[100:101]
	v_lshrrev_b32_e32 v100, 16, v98
	v_cndmask_b32_e32 v93, 0, v228, vcc
	v_add_f32_e32 v92, v92, v93
	v_exp_f32_e32 v92, v92
	v_pk_add_f32 v[94:95], v[158:159], v[94:95]
	v_cndmask_b32_e32 v93, 0, v205, vcc
	v_cmp_gt_f32_e32 vcc, s20, v189
	v_pk_add_f32 v[94:95], v[110:111], v[94:95]
	v_ldexp_f32 v174, v92, v93
	v_cndmask_b32_e32 v92, 0, v228, vcc
	v_pk_add_f32 v[94:95], v[160:161], v[94:95]
	v_add_f32_e32 v92, v189, v92
	v_pk_add_f32 v[94:95], v[162:163], v[94:95]
	v_exp_f32_e32 v92, v92
	v_pk_add_f32 v[94:95], v[164:165], v[94:95]
; template <bool SAMPLE>
; DEVI void attn_item(const Params& p, int l, int bq, int h, int qc, char* smem) {
;     ...
;         lrun[m] = lrun[m] * alpha + rs;
; #pragma unroll
;         for (int vt = 0; vt < 8; ++vt) { o[m][vt][0] *= alpha; o[m][vt][1] *= alpha; o[m][vt][2] *= alpha; o[m][vt][3] *= alpha; }
;         pb[m][0] = pk8(s[m][0], s[m][1]);
;         pb[m][1] = pk8(s[m][2], s[m][3]);
;       }
; #pragma unroll
;       for (int vt = 0; vt < 8; ++vt) {
; #pragma unroll
;         for (int k2 = 0; k2 < 2; ++k2) {
;           const char* vp = Vs + (vt * 16 + l15) * 144 + (k2 * 32 + quad * 4) * 2;
;           bf16x8 vf = mk8(*(const uint2*)vp, *(const uint2*)(vp + 32));
;           o[0][vt] = __builtin_amdgcn_mfma_f32_16x16x32_bf16(vf, pb[0][k2], o[0][vt], 0, 0, 0);
;           o[1][vt] = __builtin_amdgcn_mfma_f32_16x16x32_bf16(vf, pb[1][k2], o[1][vt], 0, 0, 0);
;         }
;       }
	v_cndmask_b32_e32 v93, 0, v205, vcc
	v_pk_add_f32 v[94:95], v[166:167], v[94:95]
	v_ldexp_f32 v92, v92, v93
	v_pk_add_f32 v[94:95], v[170:171], v[94:95]
	v_mov_b32_e32 v93, v176
	v_pk_add_f32 v[94:95], v[172:173], v[94:95]
	v_pk_mul_f32 v[26:27], v[26:27], v[92:93] op_sel_hi:[1,0]
	v_pk_add_f32 v[94:95], v[174:175], v[94:95]
	v_pk_mul_f32 v[24:25], v[24:25], v[92:93] op_sel_hi:[1,0]
	v_pk_fma_f32 v[140:141], v[140:141], v[92:93], v[94:95]
	v_pk_mul_f32 v[22:23], v[22:23], v[92:93] op_sel_hi:[1,0]
	v_pk_mul_f32 v[20:21], v[20:21], v[92:93] op_sel_hi:[1,0]
	v_pk_mul_f32 v[30:31], v[30:31], v[92:93] op_sel_hi:[1,0]
	v_pk_mul_f32 v[28:29], v[28:29], v[92:93] op_sel_hi:[1,0]
	v_pk_mul_f32 v[34:35], v[34:35], v[92:93] op_sel_hi:[1,0]
	v_pk_mul_f32 v[32:33], v[32:33], v[92:93] op_sel_hi:[1,0]
	v_pk_mul_f32 v[38:39], v[38:39], v[92:93] op_sel_hi:[1,0]
	v_pk_mul_f32 v[36:37], v[36:37], v[92:93] op_sel_hi:[1,0]
	v_pk_mul_f32 v[42:43], v[42:43], v[92:93] op_sel_hi:[1,0]
	v_pk_mul_f32 v[40:41], v[40:41], v[92:93] op_sel_hi:[1,0]
	v_pk_mul_f32 v[46:47], v[46:47], v[92:93] op_sel_hi:[1,0]
	v_pk_mul_f32 v[44:45], v[44:45], v[92:93] op_sel_hi:[1,0]
	v_pk_mul_f32 v[50:51], v[50:51], v[92:93] op_sel_hi:[1,0]
	v_pk_mul_f32 v[48:49], v[48:49], v[92:93] op_sel_hi:[1,0]
	v_bfe_u32 v95, v112, 16, 1
	v_add3_u32 v95, v112, v95, s33
	v_cvt_pk_bf16_f32 v99, v156, v158
	v_cvt_pk_bf16_f32 v97, v152, v114
	v_and_or_b32 v96, v95, s19, v100
	v_cvt_pk_bf16_f32 v98, v154, v108
	v_cvt_pk_bf16_f32 v93, v162, v164
	v_add3_u32 v104, s18, v184, v120
	v_add_u32_e32 v105, 0x4000, v104
	v_cvt_pk_bf16_f32 v95, v172, v174
	v_cvt_pk_bf16_f32 v94, v166, v170
	v_cvt_pk_bf16_f32 v92, v110, v160
	ds_read2_b64 v[100:103], v105 offset0:128 offset1:132
	s_waitcnt lgkmcnt(0)
	v_mfma_f32_16x16x32_bf16 v[52:55], v[100:103], v[88:91], v[52:55]
	v_mfma_f32_16x16x32_bf16 v[24:27], v[100:103], v[96:99], v[24:27]
	ds_read2_b64 v[100:103], v105 offset0:136 offset1:140
	s_waitcnt lgkmcnt(0)
	v_mfma_f32_16x16x32_bf16 v[52:55], v[100:103], v[84:87], v[52:55]
	v_mfma_f32_16x16x32_bf16 v[24:27], v[100:103], v[92:95], v[24:27]
	v_add3_u32 v100, s18, v185, v120
	v_add_u32_e32 v105, 0x4000, v100
	ds_read2_b64 v[100:103], v105 offset0:128 offset1:132
	s_waitcnt lgkmcnt(0)
	v_mfma_f32_16x16x32_bf16 v[56:59], v[100:103], v[88:91], v[56:59]
	v_mfma_f32_16x16x32_bf16 v[20:23], v[100:103], v[96:99], v[20:23]
	ds_read2_b64 v[100:103], v105 offset0:136 offset1:140
	s_waitcnt lgkmcnt(0)
	v_mfma_f32_16x16x32_bf16 v[56:59], v[100:103], v[84:87], v[56:59]
	v_mfma_f32_16x16x32_bf16 v[20:23], v[100:103], v[92:95], v[20:23]
	v_add3_u32 v100, s18, v186, v120
	v_add_u32_e32 v105, 0x4000, v100
	ds_read2_b64 v[100:103], v105 offset0:128 offset1:132
	s_waitcnt lgkmcnt(0)
	v_mfma_f32_16x16x32_bf16 v[60:63], v[100:103], v[88:91], v[60:63]
	v_mfma_f32_16x16x32_bf16 v[28:31], v[100:103], v[96:99], v[28:31]
	ds_read2_b64 v[100:103], v105 offset0:136 offset1:140
	s_waitcnt lgkmcnt(0)
	v_mfma_f32_16x16x32_bf16 v[60:63], v[100:103], v[84:87], v[60:63]
	v_mfma_f32_16x16x32_bf16 v[28:31], v[100:103], v[92:95], v[28:31]
	v_add3_u32 v100, s18, v187, v120
	v_add_u32_e32 v105, 0x4000, v100
	ds_read2_b64 v[100:103], v105 offset0:128 offset1:132
	s_waitcnt lgkmcnt(0)
	v_mfma_f32_16x16x32_bf16 v[64:67], v[100:103], v[88:91], v[64:67]
	v_mfma_f32_16x16x32_bf16 v[32:35], v[100:103], v[96:99], v[32:35]
	ds_read2_b64 v[100:103], v105 offset0:136 offset1:140
	v_add_u32_e32 v105, 0x6800, v104
	s_waitcnt lgkmcnt(0)
	v_mfma_f32_16x16x32_bf16 v[64:67], v[100:103], v[84:87], v[64:67]
	v_mfma_f32_16x16x32_bf16 v[32:35], v[100:103], v[92:95], v[32:35]
	ds_read2_b64 v[100:103], v105 offset1:4
	s_waitcnt lgkmcnt(0)
	v_mfma_f32_16x16x32_bf16 v[68:71], v[100:103], v[88:91], v[68:71]
	v_mfma_f32_16x16x32_bf16 v[36:39], v[100:103], v[96:99], v[36:39]
	ds_read2_b64 v[100:103], v105 offset0:8 offset1:12
	v_add_u32_e32 v105, 0x7000, v104
	s_waitcnt lgkmcnt(0)
	v_mfma_f32_16x16x32_bf16 v[68:71], v[100:103], v[84:87], v[68:71]
	v_mfma_f32_16x16x32_bf16 v[36:39], v[100:103], v[92:95], v[36:39]
	ds_read2_b64 v[100:103], v105 offset0:32 offset1:36
	s_waitcnt lgkmcnt(0)
	v_mfma_f32_16x16x32_bf16 v[72:75], v[100:103], v[88:91], v[72:75]
	v_mfma_f32_16x16x32_bf16 v[40:43], v[100:103], v[96:99], v[40:43]
	ds_read2_b64 v[100:103], v105 offset0:40 offset1:44
	v_add_u32_e32 v105, 0x7800, v104
	v_add_u32_e32 v104, 0x8000, v104
	s_waitcnt lgkmcnt(0)
	v_mfma_f32_16x16x32_bf16 v[72:75], v[100:103], v[84:87], v[72:75]
	v_mfma_f32_16x16x32_bf16 v[40:43], v[100:103], v[92:95], v[40:43]
	ds_read2_b64 v[100:103], v105 offset0:64 offset1:68
	s_waitcnt lgkmcnt(0)
	v_mfma_f32_16x16x32_bf16 v[76:79], v[100:103], v[88:91], v[76:79]
	v_mfma_f32_16x16x32_bf16 v[44:47], v[100:103], v[96:99], v[44:47]
	ds_read2_b64 v[100:103], v105 offset0:72 offset1:76
	s_waitcnt lgkmcnt(0)
	v_mfma_f32_16x16x32_bf16 v[76:79], v[100:103], v[84:87], v[76:79]
	v_mfma_f32_16x16x32_bf16 v[44:47], v[100:103], v[92:95], v[44:47]
	ds_read2_b64 v[100:103], v104 offset0:96 offset1:100
	s_waitcnt lgkmcnt(0)
	v_mfma_f32_16x16x32_bf16 v[80:83], v[100:103], v[88:91], v[80:83]
	ds_read2_b64 v[88:91], v104 offset0:104 offset1:108
	v_mfma_f32_16x16x32_bf16 v[48:51], v[100:103], v[96:99], v[48:51]
	s_waitcnt lgkmcnt(0)
	v_mfma_f32_16x16x32_bf16 v[80:83], v[88:91], v[84:87], v[80:83]
	v_mov_b32_e32 v84, s16
	v_mfma_f32_16x16x32_bf16 v[48:51], v[88:91], v[92:95], v[48:51]
